# grid barrier: L1 invalidate issued before the wait (overlaps arrival skew) instead of after the release
# speedup vs baseline: 1.0080x; 1.0053x over previous
; __device__ __forceinline__ unsigned xb_ld(unsigned* p)              { return __hip_atomic_load(p, __ATOMIC_RELAXED, __HIP_MEMORY_SCOPE_AGENT); }
; __device__ __forceinline__ unsigned xb_add(unsigned* p, unsigned v) { return __hip_atomic_fetch_add(p, v, __ATOMIC_RELAXED, __HIP_MEMORY_SCOPE_AGENT); }
; #define XB_SPIN(cond, bar) do { unsigned _sp = 0; while (cond) { __builtin_amdgcn_s_sleep(1); \
;     if ((++_sp & 255u) == 0u) { if (xb_ld(&(bar)[XB_TMO])) break; if (_sp > XB_SPIN_CAP) { atomicAdd(&(bar)[XB_TMO], 1u); break; } } } } while (0)
; __device__ __forceinline__ void xcd_barrier(const XcdBarrier& b) {
;     asm volatile("s_waitcnt vmcnt(0)" ::: "memory");
;     __syncthreads();
;     if (threadIdx.x == 0) {
;         unsigned* bar = b.bar;
;         __builtin_amdgcn_s_waitcnt(0);
;         unsigned nloc = b.st[0], nx = b.st[1];
;         if (nloc == 0u) { xcd_barrier_complete(bar, b.x, nloc, nx); b.st[0] = nloc; b.st[1] = nx; }
;         const unsigned old = xb_add(&bar[XB_XSUB(b.x)], 1u);
;         const unsigned gen = old / nloc;
;         if (old + 1u == (gen + 1u) * nloc) {
;             __builtin_amdgcn_fence(__ATOMIC_RELEASE, "agent");
;             asm volatile("s_waitcnt vmcnt(0)" ::: "memory");
;             const unsigned og = xb_add(&bar[XB_TOP], 1u);
;             const unsigned tg = og / nx;
;             if (og + 1u == (tg + 1u) * nx) xb_add(&bar[XB_TOPGEN], 1u);
;             else XB_SPIN(xb_ld(&bar[XB_TOPGEN]) == tg, bar);
;             __builtin_amdgcn_fence(__ATOMIC_ACQUIRE, "agent");
;             xb_add(&bar[XB_XGEN(b.x)], 1u);
;             asm volatile("s_waitcnt vmcnt(0)" ::: "memory");
;         } else {
;             XB_SPIN(xb_ld(&bar[XB_XGEN(b.x)]) == gen, bar);
;             __builtin_amdgcn_fence(__ATOMIC_ACQUIRE, "agent");
;             asm volatile("s_waitcnt vmcnt(0)" ::: "memory");
;         }
.LBB0_95:
	v_readlane_b32 s6, v253, 9
	s_lshl_b32 s6, s6, 8
	v_readlane_b32 s8, v253, 7
	v_readlane_b32 s9, v253, 8
	s_add_u32 s6, s8, s6
	s_addc_u32 s7, s9, 0
	v_mov_b32_e32 v2, 0x1000
	v_mov_b32_e32 v4, 1
	global_atomic_add v4, v2, v4, s[6:7] offset:1024 sc0
	v_cvt_f32_u32_e32 v2, v3
	v_sub_u32_e32 v5, 0, v3
	v_rcp_iflag_f32_e32 v2, v2
	s_nop 0
	v_mul_f32_e32 v2, 0x4f7ffffe, v2
	v_cvt_u32_f32_e32 v2, v2
	v_mul_lo_u32 v5, v5, v2
	v_mul_hi_u32 v5, v2, v5
	v_add_u32_e32 v2, v2, v5
	s_waitcnt vmcnt(0)
	v_mul_hi_u32 v2, v4, v2
	v_mul_lo_u32 v5, v2, v3
	v_sub_u32_e32 v5, v4, v5
	v_add_u32_e32 v6, 1, v2
	v_cmp_ge_u32_e32 vcc, v5, v3
	v_add_u32_e32 v4, 1, v4
	s_nop 0
	v_cndmask_b32_e32 v2, v2, v6, vcc
	v_sub_u32_e32 v6, v5, v3
	v_cndmask_b32_e32 v5, v5, v6, vcc
	v_add_u32_e32 v6, 1, v2
	v_cmp_ge_u32_e32 vcc, v5, v3
	s_nop 1
	v_cndmask_b32_e32 v2, v2, v6, vcc
	v_mul_lo_u32 v5, v3, v2
	v_add_u32_e32 v3, v5, v3
	v_cmp_ne_u32_e32 vcc, v4, v3
	s_and_saveexec_b64 s[8:9], vcc
	s_xor_b64 s[8:9], exec, s[8:9]
	s_cbranch_execz .LBB0_109
	s_waitcnt lgkmcnt(0)
	v_mov_b32_e32 v1, 0x2000
	buffer_inv sc1
	global_load_dword v1, v1, s[6:7] offset:1024 sc1
	s_add_u32 s24, s6, 0x2400
	s_addc_u32 s25, s7, 0
	s_waitcnt vmcnt(0)
	v_cmp_eq_u32_e32 vcc, v1, v2
	s_and_saveexec_b64 s[10:11], vcc
	s_cbranch_execz .LBB0_108
	s_add_u32 s12, s84, 0x4200
	s_addc_u32 s13, s85, 0
	s_mov_b32 s33, 1
	s_mov_b64 s[26:27], 0
	v_mov_b32_e32 v1, 0
	s_branch .LBB0_99

; __device__ __forceinline__ unsigned xb_ld(unsigned* p)              { return __hip_atomic_load(p, __ATOMIC_RELAXED, __HIP_MEMORY_SCOPE_AGENT); }
; __device__ __forceinline__ unsigned xb_add(unsigned* p, unsigned v) { return __hip_atomic_fetch_add(p, v, __ATOMIC_RELAXED, __HIP_MEMORY_SCOPE_AGENT); }
; #define XB_SPIN(cond, bar) do { unsigned _sp = 0; while (cond) { __builtin_amdgcn_s_sleep(1); \
;     if ((++_sp & 255u) == 0u) { if (xb_ld(&(bar)[XB_TMO])) break; if (_sp > XB_SPIN_CAP) { atomicAdd(&(bar)[XB_TMO], 1u); break; } } } } while (0)
; __device__ __forceinline__ void xcd_barrier(const XcdBarrier& b) {
;     ...
;         const unsigned old = xb_add(&bar[XB_XSUB(b.x)], 1u);
;         const unsigned gen = old / nloc;
;         if (old + 1u == (gen + 1u) * nloc) {
;             __builtin_amdgcn_fence(__ATOMIC_RELEASE, "agent");
;             asm volatile("s_waitcnt vmcnt(0)" ::: "memory");
;             const unsigned og = xb_add(&bar[XB_TOP], 1u);
;             const unsigned tg = og / nx;
;             if (og + 1u == (tg + 1u) * nx) xb_add(&bar[XB_TOPGEN], 1u);
;             else XB_SPIN(xb_ld(&bar[XB_TOPGEN]) == tg, bar);
;             __builtin_amdgcn_fence(__ATOMIC_ACQUIRE, "agent");
;             xb_add(&bar[XB_XGEN(b.x)], 1u);
;             asm volatile("s_waitcnt vmcnt(0)" ::: "memory");
;         } else {
;             XB_SPIN(xb_ld(&bar[XB_XGEN(b.x)]) == gen, bar);
;             __builtin_amdgcn_fence(__ATOMIC_ACQUIRE, "agent");
;             asm volatile("s_waitcnt vmcnt(0)" ::: "memory");
.LBB0_108:
	s_or_b64 exec, exec, s[10:11]
	s_waitcnt vmcnt(0)
	s_waitcnt vmcnt(0)
.LBB0_109:
	s_andn2_saveexec_b64 s[8:9], s[8:9]
	s_cbranch_execz .LBB0_127
	s_mov_b64 s[8:9], exec
	buffer_wbl2 sc1
	buffer_inv sc1
	s_waitcnt lgkmcnt(0)
	s_waitcnt vmcnt(0)
	v_mbcnt_lo_u32_b32 v2, s8, 0
	v_mbcnt_hi_u32_b32 v2, s9, v2
	v_cmp_eq_u32_e32 vcc, 0, v2
	s_and_saveexec_b64 s[10:11], vcc
	s_cbranch_execz .LBB0_112
	s_bcnt1_i32_b64 s8, s[8:9]
	v_mov_b32_e32 v3, 0x7000
	v_mov_b32_e32 v4, s8
	global_atomic_add v3, v3, v4, s[84:85] offset:1024 sc0

; __device__ __forceinline__ unsigned xb_ld(unsigned* p)              { return __hip_atomic_load(p, __ATOMIC_RELAXED, __HIP_MEMORY_SCOPE_AGENT); }
; __device__ __forceinline__ unsigned xb_add(unsigned* p, unsigned v) { return __hip_atomic_fetch_add(p, v, __ATOMIC_RELAXED, __HIP_MEMORY_SCOPE_AGENT); }
; #define XB_SPIN(cond, bar) do { unsigned _sp = 0; while (cond) { __builtin_amdgcn_s_sleep(1); \
;     if ((++_sp & 255u) == 0u) { if (xb_ld(&(bar)[XB_TMO])) break; if (_sp > XB_SPIN_CAP) { atomicAdd(&(bar)[XB_TMO], 1u); break; } } } } while (0)
; __device__ __forceinline__ void xcd_barrier(const XcdBarrier& b) {
;     ...
;             const unsigned og = xb_add(&bar[XB_TOP], 1u);
;             const unsigned tg = og / nx;
;             if (og + 1u == (tg + 1u) * nx) xb_add(&bar[XB_TOPGEN], 1u);
;             else XB_SPIN(xb_ld(&bar[XB_TOPGEN]) == tg, bar);
;             __builtin_amdgcn_fence(__ATOMIC_ACQUIRE, "agent");
;             xb_add(&bar[XB_XGEN(b.x)], 1u);
;             asm volatile("s_waitcnt vmcnt(0)" ::: "memory");
.LBB0_126:
	s_or_b64 exec, exec, s[8:9]
	v_mov_b32_e32 v1, 0x2000
	v_mov_b32_e32 v2, 1
	s_waitcnt vmcnt(0)
	global_atomic_add v1, v2, s[6:7] offset:1024
	s_waitcnt vmcnt(0)

; __device__ __forceinline__ unsigned xb_ld(unsigned* p)              { return __hip_atomic_load(p, __ATOMIC_RELAXED, __HIP_MEMORY_SCOPE_AGENT); }
; __device__ __forceinline__ unsigned xb_add(unsigned* p, unsigned v) { return __hip_atomic_fetch_add(p, v, __ATOMIC_RELAXED, __HIP_MEMORY_SCOPE_AGENT); }
; #define XB_SPIN(cond, bar) do { unsigned _sp = 0; while (cond) { __builtin_amdgcn_s_sleep(1); \
;     if ((++_sp & 255u) == 0u) { if (xb_ld(&(bar)[XB_TMO])) break; if (_sp > XB_SPIN_CAP) { atomicAdd(&(bar)[XB_TMO], 1u); break; } } } } while (0)
; __device__ __forceinline__ void xcd_barrier(const XcdBarrier& b) {
;     asm volatile("s_waitcnt vmcnt(0)" ::: "memory");
;     __syncthreads();
;     if (threadIdx.x == 0) {
;         unsigned* bar = b.bar;
;         __builtin_amdgcn_s_waitcnt(0);
;         unsigned nloc = b.st[0], nx = b.st[1];
;         if (nloc == 0u) { xcd_barrier_complete(bar, b.x, nloc, nx); b.st[0] = nloc; b.st[1] = nx; }
;         const unsigned old = xb_add(&bar[XB_XSUB(b.x)], 1u);
;         const unsigned gen = old / nloc;
;         if (old + 1u == (gen + 1u) * nloc) {
;             __builtin_amdgcn_fence(__ATOMIC_RELEASE, "agent");
;             asm volatile("s_waitcnt vmcnt(0)" ::: "memory");
;             const unsigned og = xb_add(&bar[XB_TOP], 1u);
;             const unsigned tg = og / nx;
;             if (og + 1u == (tg + 1u) * nx) xb_add(&bar[XB_TOPGEN], 1u);
;             else XB_SPIN(xb_ld(&bar[XB_TOPGEN]) == tg, bar);
;             __builtin_amdgcn_fence(__ATOMIC_ACQUIRE, "agent");
;             xb_add(&bar[XB_XGEN(b.x)], 1u);
;             asm volatile("s_waitcnt vmcnt(0)" ::: "memory");
;         } else {
;             XB_SPIN(xb_ld(&bar[XB_XGEN(b.x)]) == gen, bar);
;             __builtin_amdgcn_fence(__ATOMIC_ACQUIRE, "agent");
;             asm volatile("s_waitcnt vmcnt(0)" ::: "memory");
;         }
.LBB0_179:
	v_readlane_b32 s4, v253, 9
	s_lshl_b32 s4, s4, 8
	v_readlane_b32 s6, v253, 7
	v_readlane_b32 s7, v253, 8
	s_add_u32 s4, s6, s4
	s_addc_u32 s5, s7, 0
	v_mov_b32_e32 v2, 0x1000
	v_mov_b32_e32 v4, 1
	global_atomic_add v4, v2, v4, s[4:5] offset:1024 sc0
	v_cvt_f32_u32_e32 v2, v3
	v_sub_u32_e32 v5, 0, v3
	v_rcp_iflag_f32_e32 v2, v2
	s_nop 0
	v_mul_f32_e32 v2, 0x4f7ffffe, v2
	v_cvt_u32_f32_e32 v2, v2
	v_mul_lo_u32 v5, v5, v2
	v_mul_hi_u32 v5, v2, v5
	v_add_u32_e32 v2, v2, v5
	s_waitcnt vmcnt(0)
	v_mul_hi_u32 v2, v4, v2
	v_mul_lo_u32 v5, v2, v3
	v_sub_u32_e32 v5, v4, v5
	v_add_u32_e32 v6, 1, v2
	v_cmp_ge_u32_e32 vcc, v5, v3
	v_add_u32_e32 v4, 1, v4
	s_nop 0
	v_cndmask_b32_e32 v2, v2, v6, vcc
	v_sub_u32_e32 v6, v5, v3
	v_cndmask_b32_e32 v5, v5, v6, vcc
	v_add_u32_e32 v6, 1, v2
	v_cmp_ge_u32_e32 vcc, v5, v3
	s_nop 1
	v_cndmask_b32_e32 v2, v2, v6, vcc
	v_mul_lo_u32 v5, v3, v2
	v_add_u32_e32 v3, v5, v3
	v_cmp_ne_u32_e32 vcc, v4, v3
	s_and_saveexec_b64 s[6:7], vcc
	s_xor_b64 s[6:7], exec, s[6:7]
	s_cbranch_execz .LBB0_193
	s_waitcnt lgkmcnt(0)
	v_mov_b32_e32 v1, 0x2000
	buffer_inv sc1
	global_load_dword v1, v1, s[4:5] offset:1024 sc1
	s_add_u32 s12, s4, 0x2400
	s_addc_u32 s13, s5, 0
	s_waitcnt vmcnt(0)
	v_cmp_eq_u32_e32 vcc, v1, v2
	s_and_saveexec_b64 s[8:9], vcc
	s_cbranch_execz .LBB0_192
	s_add_u32 s10, s84, 0x4200
	s_addc_u32 s11, s85, 0
	s_mov_b32 s28, 1
	s_mov_b64 s[14:15], 0
	v_mov_b32_e32 v1, 0
	s_branch .LBB0_183

; __device__ __forceinline__ unsigned xb_ld(unsigned* p)              { return __hip_atomic_load(p, __ATOMIC_RELAXED, __HIP_MEMORY_SCOPE_AGENT); }
; __device__ __forceinline__ unsigned xb_add(unsigned* p, unsigned v) { return __hip_atomic_fetch_add(p, v, __ATOMIC_RELAXED, __HIP_MEMORY_SCOPE_AGENT); }
; #define XB_SPIN(cond, bar) do { unsigned _sp = 0; while (cond) { __builtin_amdgcn_s_sleep(1); \
;     if ((++_sp & 255u) == 0u) { if (xb_ld(&(bar)[XB_TMO])) break; if (_sp > XB_SPIN_CAP) { atomicAdd(&(bar)[XB_TMO], 1u); break; } } } } while (0)
; __device__ __forceinline__ void xcd_barrier(const XcdBarrier& b) {
;     ...
;         const unsigned old = xb_add(&bar[XB_XSUB(b.x)], 1u);
;         const unsigned gen = old / nloc;
;         if (old + 1u == (gen + 1u) * nloc) {
;             __builtin_amdgcn_fence(__ATOMIC_RELEASE, "agent");
;             asm volatile("s_waitcnt vmcnt(0)" ::: "memory");
;             const unsigned og = xb_add(&bar[XB_TOP], 1u);
;             const unsigned tg = og / nx;
;             if (og + 1u == (tg + 1u) * nx) xb_add(&bar[XB_TOPGEN], 1u);
;             else XB_SPIN(xb_ld(&bar[XB_TOPGEN]) == tg, bar);
;             __builtin_amdgcn_fence(__ATOMIC_ACQUIRE, "agent");
;             xb_add(&bar[XB_XGEN(b.x)], 1u);
;             asm volatile("s_waitcnt vmcnt(0)" ::: "memory");
;         } else {
;             XB_SPIN(xb_ld(&bar[XB_XGEN(b.x)]) == gen, bar);
;             __builtin_amdgcn_fence(__ATOMIC_ACQUIRE, "agent");
;             asm volatile("s_waitcnt vmcnt(0)" ::: "memory");
.LBB0_192:
	s_or_b64 exec, exec, s[8:9]
	s_waitcnt vmcnt(0)
	s_waitcnt vmcnt(0)
.LBB0_193:
	s_andn2_saveexec_b64 s[6:7], s[6:7]
	s_cbranch_execz .LBB0_211
	s_mov_b64 s[6:7], exec
	buffer_wbl2 sc1
	buffer_inv sc1
	s_waitcnt lgkmcnt(0)
	s_waitcnt vmcnt(0)
	v_mbcnt_lo_u32_b32 v2, s6, 0
	v_mbcnt_hi_u32_b32 v2, s7, v2
	v_cmp_eq_u32_e32 vcc, 0, v2
	s_and_saveexec_b64 s[8:9], vcc
	s_cbranch_execz .LBB0_196
	s_bcnt1_i32_b64 s6, s[6:7]
	v_mov_b32_e32 v3, 0x7000
	v_mov_b32_e32 v4, s6
	global_atomic_add v3, v3, v4, s[84:85] offset:1024 sc0

; __device__ __forceinline__ unsigned xb_ld(unsigned* p)              { return __hip_atomic_load(p, __ATOMIC_RELAXED, __HIP_MEMORY_SCOPE_AGENT); }
; __device__ __forceinline__ unsigned xb_add(unsigned* p, unsigned v) { return __hip_atomic_fetch_add(p, v, __ATOMIC_RELAXED, __HIP_MEMORY_SCOPE_AGENT); }
; #define XB_SPIN(cond, bar) do { unsigned _sp = 0; while (cond) { __builtin_amdgcn_s_sleep(1); \
;     if ((++_sp & 255u) == 0u) { if (xb_ld(&(bar)[XB_TMO])) break; if (_sp > XB_SPIN_CAP) { atomicAdd(&(bar)[XB_TMO], 1u); break; } } } } while (0)
; __device__ __forceinline__ void xcd_barrier(const XcdBarrier& b) {
;     ...
;             const unsigned og = xb_add(&bar[XB_TOP], 1u);
;             const unsigned tg = og / nx;
;             if (og + 1u == (tg + 1u) * nx) xb_add(&bar[XB_TOPGEN], 1u);
;             else XB_SPIN(xb_ld(&bar[XB_TOPGEN]) == tg, bar);
;             __builtin_amdgcn_fence(__ATOMIC_ACQUIRE, "agent");
;             xb_add(&bar[XB_XGEN(b.x)], 1u);
;             asm volatile("s_waitcnt vmcnt(0)" ::: "memory");
.LBB0_210:
	s_or_b64 exec, exec, s[6:7]
	v_mov_b32_e32 v1, 0x2000
	v_mov_b32_e32 v2, 1
	s_waitcnt vmcnt(0)
	global_atomic_add v1, v2, s[4:5] offset:1024
	s_waitcnt vmcnt(0)

; __device__ __forceinline__ unsigned xb_ld(unsigned* p)              { return __hip_atomic_load(p, __ATOMIC_RELAXED, __HIP_MEMORY_SCOPE_AGENT); }
; __device__ __forceinline__ unsigned xb_add(unsigned* p, unsigned v) { return __hip_atomic_fetch_add(p, v, __ATOMIC_RELAXED, __HIP_MEMORY_SCOPE_AGENT); }
; #define XB_SPIN(cond, bar) do { unsigned _sp = 0; while (cond) { __builtin_amdgcn_s_sleep(1); \
;     if ((++_sp & 255u) == 0u) { if (xb_ld(&(bar)[XB_TMO])) break; if (_sp > XB_SPIN_CAP) { atomicAdd(&(bar)[XB_TMO], 1u); break; } } } } while (0)
; __device__ __forceinline__ void xcd_barrier(const XcdBarrier& b) {
;     asm volatile("s_waitcnt vmcnt(0)" ::: "memory");
;     __syncthreads();
;     if (threadIdx.x == 0) {
;         unsigned* bar = b.bar;
;         __builtin_amdgcn_s_waitcnt(0);
;         unsigned nloc = b.st[0], nx = b.st[1];
;         if (nloc == 0u) { xcd_barrier_complete(bar, b.x, nloc, nx); b.st[0] = nloc; b.st[1] = nx; }
;         const unsigned old = xb_add(&bar[XB_XSUB(b.x)], 1u);
;         const unsigned gen = old / nloc;
;         if (old + 1u == (gen + 1u) * nloc) {
;             __builtin_amdgcn_fence(__ATOMIC_RELEASE, "agent");
;             asm volatile("s_waitcnt vmcnt(0)" ::: "memory");
;             const unsigned og = xb_add(&bar[XB_TOP], 1u);
;             const unsigned tg = og / nx;
;             if (og + 1u == (tg + 1u) * nx) xb_add(&bar[XB_TOPGEN], 1u);
;             else XB_SPIN(xb_ld(&bar[XB_TOPGEN]) == tg, bar);
;             __builtin_amdgcn_fence(__ATOMIC_ACQUIRE, "agent");
;             xb_add(&bar[XB_XGEN(b.x)], 1u);
;             asm volatile("s_waitcnt vmcnt(0)" ::: "memory");
;         } else {
;             XB_SPIN(xb_ld(&bar[XB_XGEN(b.x)]) == gen, bar);
;             __builtin_amdgcn_fence(__ATOMIC_ACQUIRE, "agent");
;             asm volatile("s_waitcnt vmcnt(0)" ::: "memory");
;         }
.LBB0_585:
	v_readlane_b32 s4, v253, 9
	s_lshl_b32 s4, s4, 8
	v_readlane_b32 s6, v253, 7
	v_readlane_b32 s7, v253, 8
	s_add_u32 s4, s6, s4
	s_addc_u32 s5, s7, 0
	v_mov_b32_e32 v2, 0x1000
	v_mov_b32_e32 v4, 1
	global_atomic_add v4, v2, v4, s[4:5] offset:1024 sc0
	v_cvt_f32_u32_e32 v2, v3
	v_sub_u32_e32 v5, 0, v3
	v_rcp_iflag_f32_e32 v2, v2
	s_nop 0
	v_mul_f32_e32 v2, 0x4f7ffffe, v2
	v_cvt_u32_f32_e32 v2, v2
	v_mul_lo_u32 v5, v5, v2
	v_mul_hi_u32 v5, v2, v5
	v_add_u32_e32 v2, v2, v5
	s_waitcnt vmcnt(0)
	v_mul_hi_u32 v2, v4, v2
	v_mul_lo_u32 v5, v2, v3
	v_sub_u32_e32 v5, v4, v5
	v_add_u32_e32 v6, 1, v2
	v_cmp_ge_u32_e32 vcc, v5, v3
	v_add_u32_e32 v4, 1, v4
	s_nop 0
	v_cndmask_b32_e32 v2, v2, v6, vcc
	v_sub_u32_e32 v6, v5, v3
	v_cndmask_b32_e32 v5, v5, v6, vcc
	v_add_u32_e32 v6, 1, v2
	v_cmp_ge_u32_e32 vcc, v5, v3
	s_nop 1
	v_cndmask_b32_e32 v2, v2, v6, vcc
	v_mul_lo_u32 v5, v3, v2
	v_add_u32_e32 v3, v5, v3
	v_cmp_ne_u32_e32 vcc, v4, v3
	s_and_saveexec_b64 s[6:7], vcc
	s_xor_b64 s[6:7], exec, s[6:7]
	s_cbranch_execz .LBB0_599
	s_waitcnt lgkmcnt(0)
	v_mov_b32_e32 v1, 0x2000
	buffer_inv sc1
	global_load_dword v1, v1, s[4:5] offset:1024 sc1
	s_add_u32 s12, s4, 0x2400
	s_addc_u32 s13, s5, 0
	s_waitcnt vmcnt(0)
	v_cmp_eq_u32_e32 vcc, v1, v2
	s_and_saveexec_b64 s[8:9], vcc
	s_cbranch_execz .LBB0_598
	s_add_u32 s10, s84, 0x4200
	s_addc_u32 s11, s85, 0
	s_mov_b32 s24, 1
	s_mov_b64 s[14:15], 0
	v_mov_b32_e32 v1, 0
	s_branch .LBB0_589

; __device__ __forceinline__ unsigned xb_ld(unsigned* p)              { return __hip_atomic_load(p, __ATOMIC_RELAXED, __HIP_MEMORY_SCOPE_AGENT); }
; __device__ __forceinline__ unsigned xb_add(unsigned* p, unsigned v) { return __hip_atomic_fetch_add(p, v, __ATOMIC_RELAXED, __HIP_MEMORY_SCOPE_AGENT); }
; #define XB_SPIN(cond, bar) do { unsigned _sp = 0; while (cond) { __builtin_amdgcn_s_sleep(1); \
;     if ((++_sp & 255u) == 0u) { if (xb_ld(&(bar)[XB_TMO])) break; if (_sp > XB_SPIN_CAP) { atomicAdd(&(bar)[XB_TMO], 1u); break; } } } } while (0)
; __device__ __forceinline__ void xcd_barrier(const XcdBarrier& b) {
;     asm volatile("s_waitcnt vmcnt(0)" ::: "memory");
;     __syncthreads();
;     if (threadIdx.x == 0) {
;         unsigned* bar = b.bar;
;         __builtin_amdgcn_s_waitcnt(0);
;         unsigned nloc = b.st[0], nx = b.st[1];
;         if (nloc == 0u) { xcd_barrier_complete(bar, b.x, nloc, nx); b.st[0] = nloc; b.st[1] = nx; }
;         const unsigned old = xb_add(&bar[XB_XSUB(b.x)], 1u);
;         const unsigned gen = old / nloc;
;         if (old + 1u == (gen + 1u) * nloc) {
;             __builtin_amdgcn_fence(__ATOMIC_RELEASE, "agent");
;             asm volatile("s_waitcnt vmcnt(0)" ::: "memory");
;             const unsigned og = xb_add(&bar[XB_TOP], 1u);
;             const unsigned tg = og / nx;
;             if (og + 1u == (tg + 1u) * nx) xb_add(&bar[XB_TOPGEN], 1u);
;             else XB_SPIN(xb_ld(&bar[XB_TOPGEN]) == tg, bar);
;             __builtin_amdgcn_fence(__ATOMIC_ACQUIRE, "agent");
;             xb_add(&bar[XB_XGEN(b.x)], 1u);
;             asm volatile("s_waitcnt vmcnt(0)" ::: "memory");
;         } else {
;             XB_SPIN(xb_ld(&bar[XB_XGEN(b.x)]) == gen, bar);
;             __builtin_amdgcn_fence(__ATOMIC_ACQUIRE, "agent");
;             asm volatile("s_waitcnt vmcnt(0)" ::: "memory");
;         }
.LBB0_1226:
	v_readlane_b32 s4, v253, 9
	s_lshl_b32 s4, s4, 8
	v_readlane_b32 s6, v253, 7
	v_readlane_b32 s7, v253, 8
	s_add_u32 s4, s6, s4
	s_addc_u32 s5, s7, 0
	v_mov_b32_e32 v3, 0x1000
	v_mov_b32_e32 v5, 1
	global_atomic_add v5, v3, v5, s[4:5] offset:1024 sc0
	v_cvt_f32_u32_e32 v3, v4
	v_sub_u32_e32 v6, 0, v4
	v_rcp_iflag_f32_e32 v3, v3
	s_nop 0
	v_mul_f32_e32 v3, 0x4f7ffffe, v3
	v_cvt_u32_f32_e32 v3, v3
	v_mul_lo_u32 v6, v6, v3
	v_mul_hi_u32 v6, v3, v6
	v_add_u32_e32 v3, v3, v6
	s_waitcnt vmcnt(0)
	v_mul_hi_u32 v3, v5, v3
	v_mul_lo_u32 v6, v3, v4
	v_sub_u32_e32 v6, v5, v6
	v_add_u32_e32 v7, 1, v3
	v_cmp_ge_u32_e32 vcc, v6, v4
	v_add_u32_e32 v5, 1, v5
	s_nop 0
	v_cndmask_b32_e32 v3, v3, v7, vcc
	v_sub_u32_e32 v7, v6, v4
	v_cndmask_b32_e32 v6, v6, v7, vcc
	v_add_u32_e32 v7, 1, v3
	v_cmp_ge_u32_e32 vcc, v6, v4
	s_nop 1
	v_cndmask_b32_e32 v3, v3, v7, vcc
	v_mul_lo_u32 v6, v4, v3
	v_add_u32_e32 v4, v6, v4
	v_cmp_ne_u32_e32 vcc, v5, v4
	s_and_saveexec_b64 s[6:7], vcc
	s_xor_b64 s[6:7], exec, s[6:7]
	s_cbranch_execz .LBB0_1240
	s_waitcnt lgkmcnt(0)
	v_mov_b32_e32 v2, 0x2000
	buffer_inv sc1
	global_load_dword v2, v2, s[4:5] offset:1024 sc1
	s_add_u32 s12, s4, 0x2400
	s_addc_u32 s13, s5, 0
	s_waitcnt vmcnt(0)
	v_cmp_eq_u32_e32 vcc, v2, v3
	s_and_saveexec_b64 s[8:9], vcc
	s_cbranch_execz .LBB0_1239
	s_add_u32 s10, s84, 0x4200
	s_addc_u32 s11, s85, 0
	s_mov_b32 s24, 1
	s_mov_b64 s[14:15], 0
	v_mov_b32_e32 v2, 0
	s_branch .LBB0_1230

; __device__ __forceinline__ unsigned xb_ld(unsigned* p)              { return __hip_atomic_load(p, __ATOMIC_RELAXED, __HIP_MEMORY_SCOPE_AGENT); }
; __device__ __forceinline__ unsigned xb_add(unsigned* p, unsigned v) { return __hip_atomic_fetch_add(p, v, __ATOMIC_RELAXED, __HIP_MEMORY_SCOPE_AGENT); }
; #define XB_SPIN(cond, bar) do { unsigned _sp = 0; while (cond) { __builtin_amdgcn_s_sleep(1); \
;     if ((++_sp & 255u) == 0u) { if (xb_ld(&(bar)[XB_TMO])) break; if (_sp > XB_SPIN_CAP) { atomicAdd(&(bar)[XB_TMO], 1u); break; } } } } while (0)
; __device__ __forceinline__ void xcd_barrier(const XcdBarrier& b) {
;     ...
;         const unsigned old = xb_add(&bar[XB_XSUB(b.x)], 1u);
;         const unsigned gen = old / nloc;
;         if (old + 1u == (gen + 1u) * nloc) {
;             __builtin_amdgcn_fence(__ATOMIC_RELEASE, "agent");
;             asm volatile("s_waitcnt vmcnt(0)" ::: "memory");
;             const unsigned og = xb_add(&bar[XB_TOP], 1u);
;             const unsigned tg = og / nx;
;             if (og + 1u == (tg + 1u) * nx) xb_add(&bar[XB_TOPGEN], 1u);
;             else XB_SPIN(xb_ld(&bar[XB_TOPGEN]) == tg, bar);
;             __builtin_amdgcn_fence(__ATOMIC_ACQUIRE, "agent");
.LBB0_1240:
	s_andn2_saveexec_b64 s[6:7], s[6:7]
	s_cbranch_execz .LBB0_1258
	s_mov_b64 s[6:7], exec
	buffer_wbl2 sc1
	buffer_inv sc1
	s_waitcnt lgkmcnt(0)
	s_waitcnt vmcnt(0)
	v_mbcnt_lo_u32_b32 v3, s6, 0
	v_mbcnt_hi_u32_b32 v3, s7, v3
	v_cmp_eq_u32_e32 vcc, 0, v3
	s_and_saveexec_b64 s[8:9], vcc
	s_cbranch_execz .LBB0_1243
	s_bcnt1_i32_b64 s6, s[6:7]
	v_mov_b32_e32 v4, 0x7000
	v_mov_b32_e32 v5, s6
	global_atomic_add v4, v4, v5, s[84:85] offset:1024 sc0

; __device__ __forceinline__ unsigned xb_ld(unsigned* p)              { return __hip_atomic_load(p, __ATOMIC_RELAXED, __HIP_MEMORY_SCOPE_AGENT); }
; __device__ __forceinline__ unsigned xb_add(unsigned* p, unsigned v) { return __hip_atomic_fetch_add(p, v, __ATOMIC_RELAXED, __HIP_MEMORY_SCOPE_AGENT); }
; #define XB_SPIN(cond, bar) do { unsigned _sp = 0; while (cond) { __builtin_amdgcn_s_sleep(1); \
;     if ((++_sp & 255u) == 0u) { if (xb_ld(&(bar)[XB_TMO])) break; if (_sp > XB_SPIN_CAP) { atomicAdd(&(bar)[XB_TMO], 1u); break; } } } } while (0)
; __device__ __forceinline__ void xcd_barrier(const XcdBarrier& b) {
;     ...
;             const unsigned og = xb_add(&bar[XB_TOP], 1u);
;             const unsigned tg = og / nx;
;             if (og + 1u == (tg + 1u) * nx) xb_add(&bar[XB_TOPGEN], 1u);
;             else XB_SPIN(xb_ld(&bar[XB_TOPGEN]) == tg, bar);
;             __builtin_amdgcn_fence(__ATOMIC_ACQUIRE, "agent");
;             xb_add(&bar[XB_XGEN(b.x)], 1u);
;             asm volatile("s_waitcnt vmcnt(0)" ::: "memory");
.LBB0_1257:
	s_or_b64 exec, exec, s[6:7]
	v_mov_b32_e32 v2, 0x2000
	v_mov_b32_e32 v3, 1
	s_waitcnt vmcnt(0)
	global_atomic_add v2, v3, s[4:5] offset:1024
	s_waitcnt vmcnt(0)
